# cvhost: 16 rows x 32 cols per slot, 16-B row loads, per-wave 1 KiB LDS transpose, full 32-B sector stores (dwordx2)
# speedup vs baseline: 1.0175x; 1.0175x over previous
; #define GAS __attribute__((address_space(1)))
; __device__ __forceinline__ unsigned cvt_pk_bf16(float lo, float hi) { unsigned r; asm volatile("v_cvt_pk_bf16_f32 %0, %1, %2" : "=v"(r) : "v"(lo), "v"(hi)); return r; }
; template <int NB>
; __device__ __forceinline__ void p0_batch(int it0, int stride, int lane, const P0Ptrs& a) {
;     ...
;     for (int q = 0; q < NB; ++q) {
;         const float gs = d[q].gs; const bool hk = d[q].ks != nullptr;
;         const f32x4 t0 = hk ? s0[q] * gs : (f32x4){gs, gs, gs, gs}, t1 = hk ? s1[q] * gs : (f32x4){gs, gs, gs, gs};
; #pragma unroll
;         for (int i = 0; i < 4; ++i) { v[q][i] *= t0[i]; v[q][4 + i] *= t1[i]; }
;         if (d[q].dst) {
; #pragma unroll
;             for (int e = 0; e < 4; ++e) { u32x4 o; o.x = cvt_pk_bf16(v[q][0][e], v[q][1][e]); o.y = cvt_pk_bf16(v[q][2][e], v[q][3][e]); o.z = cvt_pk_bf16(v[q][4][e], v[q][5][e]); o.w = cvt_pk_bf16(v[q][6][e], v[q][7][e]);
;                 *(GAS u32x4*)(d[q].dst + (size_t)e * d[q].ldt) = o; } }
;     }
.LBB0_759:
	v_lshl_add_u64 v[112:113], s[28:29], 0, v[146:147]
	s_mov_b64 s[54:55], 0x18fc0000
	s_mov_b32 m0, s78
	v_lshl_add_u64 v[100:101], v[112:113], 0, s[54:55]
	s_waitcnt vmcnt(0)
	s_barrier
	global_load_lds_dwordx4 v[100:101], off
	v_lshl_add_u64 v[100:101], v[112:113], 0, s[38:39]
	s_add_i32 m0, s78, 0x2000
	v_lshl_add_u64 v[136:137], s[28:29], 0, v[144:145]
	global_load_lds_dwordx4 v[100:101], off
	v_lshl_add_u64 v[100:101], v[136:137], 0, s[40:41]
	s_add_i32 m0, s78, 0x4000
	v_lshl_add_u64 v[134:135], s[28:29], 0, v[148:149]
	global_load_lds_dwordx4 v[100:101], off
	v_lshl_add_u64 v[100:101], v[134:135], 0, s[42:43]
	s_mov_b32 m0, s58
	global_load_lds_dwordx4 v[100:101], off
	v_lshl_add_u64 v[100:101], v[134:135], 0, s[44:45]
	s_mov_b32 m0, s77
	global_load_lds_dwordx4 v[100:101], off
	s_cmp_gt_u32 s87, 20
	s_cbranch_scc1 .Lcv_done
	s_cmp_eq_u32 s87, 0
	s_cbranch_scc1 .Lcv_nocons
	s_cmp_gt_u32 s32, 6
	s_cbranch_scc1 .Lcv_nomul
	v_mul_f32_e32 v238, v237, v238
	v_mul_f32_e32 v239, v237, v239
	v_mul_f32_e32 v240, v237, v240
	v_mul_f32_e32 v241, v237, v241
	v_mul_f32_e32 v242, v237, v242
	v_mul_f32_e32 v243, v237, v243
	v_mul_f32_e32 v244, v237, v244
	v_mul_f32_e32 v245, v237, v245
.Lcv_nomul:
	v_readfirstlane_b32 s98, v0
	v_and_b32_e32 v76, 63, v0
	v_lshrrev_b32_e32 v77, 2, v76
	v_and_b32_e32 v78, 3, v76
	s_lshr_b32 s98, s98, 6
	s_lshl_b32 s99, s98, 10
	s_cmp_lt_u32 s98, 6
	s_mov_b32 s98, 0x24c00
	s_cselect_b32 s98, 0x1e800, s98
	s_add_i32 s98, s98, s99
	v_lshlrev_b32_e32 v81, 8, v78
	v_lshl_add_u32 v81, v77, 2, v81
	v_add_u32_e32 v81, s98, v81
	v_lshl_add_u32 v82, v76, 4, s98
	v_lshlrev_b32_e32 v83, 3, v78
	v_mad_u32_u24 v83, v77, s91, v83
	ds_write_b32 v81, v238
	ds_write_b32 v81, v239 offset:64
	ds_write_b32 v81, v240 offset:128
	ds_write_b32 v81, v241 offset:192
	ds_read_b128 v[100:103], v82
	ds_write_b32 v81, v242
	ds_write_b32 v81, v243 offset:64
	ds_write_b32 v81, v244 offset:128
	ds_write_b32 v81, v245 offset:192
	ds_read_b128 v[104:107], v82
	s_lshl_b32 s98, s91, 4
	s_add_u32 s98, s92, s98
	s_addc_u32 s99, s93, 0
	s_waitcnt lgkmcnt(0)
	v_cvt_pk_bf16_f32 v100, v100, v101
	v_cvt_pk_bf16_f32 v101, v102, v103
	v_cvt_pk_bf16_f32 v104, v104, v105
	v_cvt_pk_bf16_f32 v105, v106, v107
	global_store_dwordx2 v83, v[100:101], s[92:93]
	global_store_dwordx2 v83, v[104:105], s[98:99]
	s_add_u32 s92, s92, 32
	s_addc_u32 s93, s93, 0

; template <int NB>
; __device__ __forceinline__ void p0_batch(int it0, int stride, int lane, const P0Ptrs& a) {
;     f32x4 v[NB][8], s0[NB], s1[NB]; P0Desc d[NB];
; #pragma unroll
;     for (int q = 0; q < NB; ++q) { const bool ok = it0 < NFAST / 4; d[q] = p0_desc(p0_super(ok ? it0 : 0, q), lane, a); if (!ok) d[q].dst = nullptr;
; #pragma unroll
;         for (int i = 0; i < 8; ++i) v[q][i] = __builtin_nontemporal_load((const f32x4*)(d[q].src + (size_t)i * d[q].nsrc));
;         const float* kp = d[q].ks ? d[q].ks : a.ffn_g;
;         s0[q] = *(const f32x4*)(kp); s1[q] = *(const f32x4*)(kp + 4); }
.Lcv_s2done:
.Lcv_loads:
	v_and_b32_e32 v76, 63, v0
	v_lshrrev_b32_e32 v77, 2, v76
	v_and_b32_e32 v78, 3, v76
	v_lshlrev_b32_e32 v78, 4, v78
	v_mad_u32_u24 v79, v77, s90, v78
	v_lshlrev_b32_e32 v80, 2, v77
	s_lshl_b32 s98, s90, 4
	global_load_dwordx4 v[238:241], v79, s[88:89] nt
	global_load_dwordx4 v[242:245], v79, s[88:89] offset:64 nt
	global_load_dword v237, v80, s[94:95]
	s_add_u32 s88, s88, s98
	s_addc_u32 s89, s89, 0
	s_add_u32 s94, s94, 64
	s_addc_u32 s95, s95, 0
	s_and_b32 s98, s87, 3
	s_cmp_lg_u32 s98, 3
	s_cbranch_scc1 .Lcv_inc
	s_cmp_gt_u32 s87, 18
	s_cbranch_scc1 .Lcv_inc
	s_add_i32 s99, s32, 1
	s_movk_i32 s98, 0x78
	s_cmp_lt_u32 s99, 7
	s_cselect_b32 s98, 0x60, s98
	s_cmp_eq_u32 s99, 0
	s_cselect_b32 s98, 0x50, s98
	s_cselect_b32 s99, 0, 0x58
	s_load_dwordx2 s[88:89], s[100:101], s98
	s_cmp_eq_u32 s99, 0
	s_cbranch_scc0 .Lcv_s1b_s
	s_bfe_u32 s99, s2, 0x50003
	s_cmp_lt_u32 s99, 16
	s_cselect_b32 s99, 64, 0x48
